# v56: v54 + software-pipelined P3b loop (next rows' loads in flight during compute, gamma hoisted) + flag polls overlapped with arrival atomics + relaxed P4/P7 drains
# speedup vs baseline: 1.0008x; 1.0008x over previous
; DI int fresh_tid(int wid_s) { int l; asm volatile("v_mbcnt_lo_u32_b32 %0, -1, 0\n\tv_mbcnt_hi_u32_b32 %0, -1, %0" : "=v"(l)); return wid_s * 64 + l; }
; DI unsigned xb_ld(unsigned* p)              { return __hip_atomic_load(p, __ATOMIC_RELAXED, __HIP_MEMORY_SCOPE_AGENT); }
; DI unsigned xb_add(unsigned* p, unsigned v) { return __hip_atomic_fetch_add(p, v, __ATOMIC_RELAXED, __HIP_MEMORY_SCOPE_AGENT); }
; #define XB_SPIN(cond, bar) do { unsigned _sp = 0; while (cond) { __builtin_amdgcn_s_sleep(1); \
;     if ((++_sp & 255u) == 0u) { if (xb_ld(&(bar)[XB_TMO])) break; if (_sp > XB_SPIN_CAP) { atomicAdd(&(bar)[XB_TMO], 1u); break; } } } } while (0)
; DI void xcd_barrier(const XcdBarrier& b, const int wid_s) {
;     asm volatile("s_waitcnt vmcnt(0)" ::: "memory");
;     __syncthreads();
;     if (fresh_tid(wid_s) == 0) {
;         unsigned* bar = b.bar;
;         __builtin_amdgcn_s_waitcnt(0);
;         unsigned nloc = b.st[0], nx = b.st[1];
;         if (nloc == 0u) { xcd_barrier_complete(bar, b.x, nloc, nx); b.st[0] = nloc; b.st[1] = nx; }
;         const unsigned old = xb_add(&bar[XB_XSUB(b.x)], 1u);
;         const unsigned gen = old / nloc;
;         if (old + 1u == (gen + 1u) * nloc) {
;             __builtin_amdgcn_fence(__ATOMIC_RELEASE, "agent");
;             asm volatile("s_waitcnt vmcnt(0)" ::: "memory");
;             const unsigned og = xb_add(&bar[XB_TOP], 1u);
;             const unsigned tg = og / nx;
;             if (og + 1u == (tg + 1u) * nx) xb_add(&bar[XB_TOPGEN], 1u);
;             else XB_SPIN(xb_ld(&bar[XB_TOPGEN]) == tg, bar);
;             __builtin_amdgcn_fence(__ATOMIC_ACQUIRE, "agent");
;             xb_add(&bar[XB_XGEN(b.x)], 1u);
;             asm volatile("s_waitcnt vmcnt(0)" ::: "memory");
;         } else {
;             XB_SPIN(xb_ld(&bar[XB_XGEN(b.x)]) == gen, bar);
;             __builtin_amdgcn_fence(__ATOMIC_ACQUIRE, "agent");
;             asm volatile("s_waitcnt vmcnt(0)" ::: "memory");
;         }
;     }
;     __syncthreads();
; __global__ void __launch_bounds__(512, 2) fwd_mega(Params P) {
;     ...
;     xcd_barrier(xbar, wid_s);
.LBB0_477:
	s_waitcnt vmcnt(0)
	v_readlane_b32 s0, v255, 29
	s_barrier
	v_mbcnt_lo_u32_b32 v0, -1, 0
	v_mbcnt_hi_u32_b32 v0, -1, v0
	s_nop 0
	v_cmp_eq_u32_e32 vcc, s0, v0
	s_and_saveexec_b64 s[0:1], vcc
	v_readlane_b32 s4, v255, 19
	v_readlane_b32 s10, v255, 25
	v_readlane_b32 s11, v255, 26
	v_readlane_b32 s8, v255, 23
	v_readlane_b32 s9, v255, 24
	s_mov_b64 s[74:75], s[10:11]
	v_readlane_b32 s88, v255, 27
	s_mov_b64 s[72:73], s[8:9]
	v_readlane_b32 s84, v255, 39
	v_readlane_b32 s89, v255, 28
	v_readlane_b32 s87, v255, 30
	v_readlane_b32 s90, v255, 34
	v_readlane_b32 s91, v255, 33
	v_readlane_b32 s5, v255, 20
	v_readlane_b32 s6, v255, 21
	v_readlane_b32 s7, v255, 22
	s_cbranch_execz .LBB0_529
	s_add_i32 s2, 0, 0x25800
	v_mov_b32_e32 v5, s2
	ds_read_b32 v6, v5
	s_lshl_b32 s4, s87, 6
	s_add_u32 s4, s4, 0x1d83d00
	s_add_u32 s4, s80, s4
	s_addc_u32 s5, s81, 0
	v_mov_b32_e32 v2, 0
	v_mov_b32_e32 v3, 1
	global_atomic_add v7, v2, v3, s[4:5] sc0
	s_add_u32 s6, s80, 0x1d83c40
	s_addc_u32 s7, s81, 0
	s_mov_b32 s12, 32
	s_cmp_lt_u32 s33, 64
	s_cbranch_scc0 .Lb3_pre
	s_add_u32 s6, s80, 0x1d83c80
	s_addc_u32 s7, s81, 0
	s_mov_b32 s12, s82
.Lb3_pre:
	global_load_dword v4, v2, s[6:7] sc1
	s_waitcnt vmcnt(0) lgkmcnt(0)
	v_readfirstlane_b32 s15, v6
	v_readfirstlane_b32 s14, v7
	s_nop 3
	s_add_i32 s14, s14, 1
	s_cmp_eq_u32 s14, s15
	s_cbranch_scc0 .Lb3_notlast
	buffer_wbl2 sc1
	s_waitcnt vmcnt(0)
	s_add_u32 s2, s80, 0x1d83c80
	s_addc_u32 s3, s81, 0
	v_mov_b32_e32 v3, s15
	global_atomic_add v2, v3, s[2:3]
.Lb3_notlast:
	s_mov_b64 s[2:3], s[6:7]
	v_readfirstlane_b32 s14, v4
	s_mov_b32 s13, 0
	s_nop 1
	s_cmp_ge_u32 s14, s12
	s_cbranch_scc1 .Lb3_go

; DI int fresh_tid(int wid_s) { int l; asm volatile("v_mbcnt_lo_u32_b32 %0, -1, 0\n\tv_mbcnt_hi_u32_b32 %0, -1, %0" : "=v"(l)); return wid_s * 64 + l; }
; DI unsigned xb_ld(unsigned* p)              { return __hip_atomic_load(p, __ATOMIC_RELAXED, __HIP_MEMORY_SCOPE_AGENT); }
; DI unsigned xb_add(unsigned* p, unsigned v) { return __hip_atomic_fetch_add(p, v, __ATOMIC_RELAXED, __HIP_MEMORY_SCOPE_AGENT); }
; #define XB_SPIN(cond, bar) do { unsigned _sp = 0; while (cond) { __builtin_amdgcn_s_sleep(1); \
;     if ((++_sp & 255u) == 0u) { if (xb_ld(&(bar)[XB_TMO])) break; if (_sp > XB_SPIN_CAP) { atomicAdd(&(bar)[XB_TMO], 1u); break; } } } } while (0)
; DI void xcd_barrier(const XcdBarrier& b, const int wid_s) {
;     asm volatile("s_waitcnt vmcnt(0)" ::: "memory");
;     __syncthreads();
;     if (fresh_tid(wid_s) == 0) {
;         unsigned* bar = b.bar;
;         __builtin_amdgcn_s_waitcnt(0);
;         unsigned nloc = b.st[0], nx = b.st[1];
;         if (nloc == 0u) { xcd_barrier_complete(bar, b.x, nloc, nx); b.st[0] = nloc; b.st[1] = nx; }
;         const unsigned old = xb_add(&bar[XB_XSUB(b.x)], 1u);
;         const unsigned gen = old / nloc;
;         if (old + 1u == (gen + 1u) * nloc) {
;             __builtin_amdgcn_fence(__ATOMIC_RELEASE, "agent");
;             asm volatile("s_waitcnt vmcnt(0)" ::: "memory");
;             const unsigned og = xb_add(&bar[XB_TOP], 1u);
;             const unsigned tg = og / nx;
;             if (og + 1u == (tg + 1u) * nx) xb_add(&bar[XB_TOPGEN], 1u);
;             else XB_SPIN(xb_ld(&bar[XB_TOPGEN]) == tg, bar);
;             __builtin_amdgcn_fence(__ATOMIC_ACQUIRE, "agent");
;             xb_add(&bar[XB_XGEN(b.x)], 1u);
;             asm volatile("s_waitcnt vmcnt(0)" ::: "memory");
;         } else {
;             XB_SPIN(xb_ld(&bar[XB_XGEN(b.x)]) == gen, bar);
;             __builtin_amdgcn_fence(__ATOMIC_ACQUIRE, "agent");
;             asm volatile("s_waitcnt vmcnt(0)" ::: "memory");
;         }
;     }
;     __syncthreads();
; __global__ void __launch_bounds__(512, 2) fwd_mega(Params P) {
;     ...
;     xcd_barrier(xbar, wid_s);
.LBB0_591:
	s_or_b64 exec, exec, s[12:13]
	s_add_u32 s2, s80, 0x1d83c00
	s_addc_u32 s3, s81, 0
	v_mov_b32_e32 v2, 0
	global_load_dword v3, v2, s[2:3] sc1
	s_waitcnt vmcnt(0)
	v_readlane_b32 s0, v255, 29
	s_barrier
	v_mbcnt_lo_u32_b32 v0, -1, 0
	v_mbcnt_hi_u32_b32 v0, -1, v0
	s_nop 0
	v_cmp_eq_u32_e32 vcc, s0, v0
	s_and_saveexec_b64 s[0:1], vcc
	s_cbranch_execz .LBB0_643
	s_add_u32 s2, s80, 0x1d83c00
	s_addc_u32 s3, s81, 0
	v_readfirstlane_b32 s5, v3
	v_mov_b32_e32 v2, 0
	s_mov_b32 s4, 0
	s_cmp_ge_u32 s5, 64
	s_cbranch_scc1 .Lp3b_go

; DI unsigned pack2(float lo, float hi) { f32x2_t v = {lo, hi}; bf16x2_t b = __builtin_convertvector(v, bf16x2_t); return __builtin_bit_cast(unsigned, b); }
; DI float bflo(unsigned w) { return __uint_as_float(w << 16); }
; DI float bfhi(unsigned w) { return __uint_as_float(w & 0xffff0000u); }
; DI float shx(float v, int mask, int lane) { return __int_as_float(__builtin_amdgcn_ds_bpermute((lane ^ mask) << 2, __float_as_int(v))); }
; DI float siluf(float x) { return x * __builtin_amdgcn_rcpf(1.f + __expf(-x)); }
; __global__ void __launch_bounds__(512, 2) fwd_mega(Params P) {
;     ...
;     { PHASE_IDS
;     for (int it = bid; it < M_TOK / 8; it += nblk) {
;         const int row = it * 8 + wave8;
;         bf16_t* mix = (bf16_t*)(ws + OFF_MIX) + (size_t)row * DM;
;         {
;             const int col = lane * 8;
;             const u32x4 ov = *(const u32x4*)((const bf16_t*)(ws + OFF_OG) + (size_t)row * 512 + col);
;             const u32x4 zv = *(const u32x4*)((const bf16_t*)(ws + OFF_Z) + (size_t)row * 512 + col);
;             float o[8] = {bflo(ov.x), bfhi(ov.x), bflo(ov.y), bfhi(ov.y), bflo(ov.z), bfhi(ov.z), bflo(ov.w), bfhi(ov.w)};
;             float z[8] = {bflo(zv.x), bfhi(zv.x), bflo(zv.y), bfhi(zv.y), bflo(zv.z), bfhi(zv.z), bflo(zv.w), bfhi(zv.w)};
;             float ss = 0.f;
; #pragma unroll
;             for (int e = 0; e < 8; ++e) ss += o[e] * o[e];
;             ss += shx(ss, 1, lane); ss += shx(ss, 2, lane); ss += shx(ss, 4, lane); ss += shx(ss, 8, lane);
;             const float sc = rsqrtf(ss * (1.f / 128.f) + 1e-6f);
;             const float* gg = P.in[8] + (col & 127);
;             float v[8];
; #pragma unroll
;             for (int e = 0; e < 8; ++e) v[e] = o[e] * sc * gg[e] * siluf(z[e]);
;             u32x4 w; w.x = pack2(v[0], v[1]); w.y = pack2(v[2], v[3]); w.z = pack2(v[4], v[5]); w.w = pack2(v[6], v[7]);
;             *(u32x4*)(mix + col) = w;
;         }
;     }
.LBB0_643:
	s_or_b64 exec, exec, s[0:1]
	s_cmpk_gt_i32 s33, 0x7ff
	s_waitcnt lgkmcnt(0)
	s_barrier
	v_mbcnt_lo_u32_b32 v4, -1, 0
	v_mbcnt_hi_u32_b32 v4, -1, v4
	s_cbranch_scc1 .LBB0_646
	v_and_b32_e32 v5, 63, v4
	v_lshlrev_b32_e32 v6, 4, v5
	v_mov_b32_e32 v7, 0
	v_add_u32_e32 v0, s84, v4
	v_lshl_add_u64 v[8:9], s[80:81], 0, v[6:7]
	s_mov_b64 s[0:1], 0x5000000
	v_lshlrev_b32_e32 v4, 5, v4
	v_ashrrev_i32_e32 v14, 6, v0
	v_lshl_add_u64 v[0:1], s[50:51], 0, v[6:7]
	v_lshl_add_u64 v[2:3], v[8:9], 0, s[0:1]
	v_lshlrev_b32_e32 v5, 2, v5
	v_and_b32_e32 v6, 0x1e0, v4
	s_mov_b64 s[0:1], 0xd800000
	v_xor_b32_e32 v10, 4, v5
	v_xor_b32_e32 v11, 8, v5
	v_xor_b32_e32 v12, 16, v5
	v_xor_b32_e32 v13, 32, v5
	v_lshl_add_u64 v[4:5], s[44:45], 0, v[6:7]
	v_lshl_add_u64 v[6:7], v[8:9], 0, s[0:1]
	v_lshl_add_u32 v8, s33, 3, v14
	s_lshl_b32 s0, s82, 3
	v_mov_b32_e32 v14, 0x358637bd
	s_mov_b32 s1, 0x800000
	s_mov_b32 s2, s33
	global_load_dwordx4 v[56:59], v[4:5], off offset:16
	global_load_dwordx4 v[60:63], v[4:5], off
	v_ashrrev_i32_e32 v9, 31, v8
	v_lshlrev_b64 v[72:73], 10, v[8:9]
	v_lshl_add_u64 v[74:75], v[0:1], 0, v[72:73]
	global_load_dwordx4 v[64:67], v[74:75], off
	v_lshl_add_u64 v[74:75], v[2:3], 0, v[72:73]
	global_load_dwordx4 v[68:71], v[74:75], off
	s_waitcnt vmcnt(0)
.LBB0_645:
	v_ashrrev_i32_e32 v9, 31, v8
	v_lshlrev_b64 v[32:33], 11, v[8:9]
	v_lshl_add_u64 v[32:33], v[6:7], 0, v[32:33]
	v_mov_b64_e32 v[16:17], v[64:65]
	v_mov_b64_e32 v[18:19], v[66:67]
	v_mov_b64_e32 v[20:21], v[68:69]
	v_mov_b64_e32 v[22:23], v[70:71]
	s_add_i32 s2, s2, s82
	v_add_u32_e32 v8, s0, v8
	s_cmpk_gt_i32 s2, 0x7ff
	s_cbranch_scc1 .Lp3b_nopref
	v_mov_b32_e32 v72, v8
	v_ashrrev_i32_e32 v73, 31, v8
	v_lshlrev_b64 v[72:73], 10, v[72:73]
	v_lshl_add_u64 v[74:75], v[0:1], 0, v[72:73]
	global_load_dwordx4 v[64:67], v[74:75], off
	v_lshl_add_u64 v[74:75], v[2:3], 0, v[72:73]
	global_load_dwordx4 v[68:71], v[74:75], off
.Lp3b_nopref:
	v_lshlrev_b32_e32 v36, 16, v23
	v_lshlrev_b32_e32 v42, 16, v16
	v_and_b32_e32 v43, 0xffff0000, v16
	v_lshlrev_b32_e32 v34, 16, v19
	v_and_b32_e32 v35, 0xffff0000, v19
	v_and_b32_e32 v37, 0xffff0000, v23
	v_lshlrev_b32_e32 v38, 16, v18
	v_and_b32_e32 v39, 0xffff0000, v18
	v_lshlrev_b32_e32 v18, 16, v22
	v_and_b32_e32 v19, 0xffff0000, v22
	v_lshlrev_b32_e32 v22, 16, v17
	v_and_b32_e32 v23, 0xffff0000, v17
	v_pk_mul_f32 v[48:49], v[42:43], v[42:43]
	v_pk_mul_f32 v[46:47], v[22:23], v[22:23]
	v_add_f32_e32 v48, v48, v49
	v_add_f32_e32 v46, v48, v46
	v_pk_mul_f32 v[44:45], v[38:39], v[38:39]
	v_add_f32_e32 v46, v46, v47
	v_add_f32_e32 v44, v46, v44
	v_lshlrev_b32_e32 v40, 16, v21
	v_and_b32_e32 v41, 0xffff0000, v21
	v_lshlrev_b32_e32 v16, 16, v20
	v_and_b32_e32 v17, 0xffff0000, v20
	v_pk_mul_f32 v[20:21], v[34:35], v[34:35]
	v_add_f32_e32 v44, v44, v45
	v_add_f32_e32 v20, v44, v20
	v_add_f32_e32 v20, v20, v21
	ds_bpermute_b32 v21, v10, v20
	v_mul_f32_e32 v9, 0xbfb8aa3b, v18
	v_exp_f32_e32 v9, v9
	v_mul_f32_e32 v15, 0xbfb8aa3b, v19
	v_exp_f32_e32 v15, v15
	s_waitcnt lgkmcnt(0)
	v_add_f32_e32 v21, v20, v21
	ds_bpermute_b32 v47, v11, v21
	v_add_f32_e32 v9, 1.0, v9
	v_rcp_f32_e32 v20, v9
	v_add_f32_e32 v15, 1.0, v15
	v_mul_f32_e32 v50, 0xbfb8aa3b, v40
	s_waitcnt lgkmcnt(0)
	v_add_f32_e32 v9, v21, v47
	ds_bpermute_b32 v47, v12, v9
	v_rcp_f32_e32 v21, v15
	v_mul_f32_e32 v51, 0xbfb8aa3b, v41
	v_exp_f32_e32 v50, v50
	v_exp_f32_e32 v51, v51
	s_waitcnt lgkmcnt(0)
	v_add_f32_e32 v9, v9, v47
	ds_bpermute_b32 v15, v13, v9
	v_mul_f32_e32 v52, 0xbfb8aa3b, v16
	v_mul_f32_e32 v53, 0xbfb8aa3b, v17
	v_mul_f32_e32 v54, 0xbfb8aa3b, v36
	v_mul_f32_e32 v55, 0xbfb8aa3b, v37
	s_waitcnt lgkmcnt(0)
	v_add_f32_e32 v9, v9, v15
	v_fmamk_f32 v9, v9, 0x3c000000, v14
	v_exp_f32_e32 v52, v52
	v_exp_f32_e32 v53, v53
	v_exp_f32_e32 v49, v54
	v_exp_f32_e32 v54, v55
	v_mul_f32_e32 v15, 0x4b800000, v9
	v_cmp_gt_f32_e32 vcc, s1, v9
	v_add_f32_e32 v44, 1.0, v50
	v_add_f32_e32 v45, 1.0, v51
	v_cndmask_b32_e32 v9, v9, v15, vcc
	v_rsq_f32_e32 v9, v9
	v_rcp_f32_e32 v44, v44
	v_rcp_f32_e32 v45, v45
	v_add_f32_e32 v46, 1.0, v52
	v_add_f32_e32 v48, 1.0, v53
	v_add_f32_e32 v49, 1.0, v49
	v_add_f32_e32 v50, 1.0, v54
	v_rcp_f32_e32 v46, v46
	v_rcp_f32_e32 v47, v48
	v_rcp_f32_e32 v48, v49
	v_rcp_f32_e32 v49, v50
	v_mul_f32_e32 v15, 0x45800000, v9
	v_pk_mul_f32 v[18:19], v[20:21], v[18:19]
	v_pk_mul_f32 v[20:21], v[44:45], v[40:41]
	v_cndmask_b32_e32 v40, v9, v15, vcc
	v_pk_mul_f32 v[42:43], v[40:41], v[42:43] op_sel_hi:[0,1]
	v_pk_mul_f32 v[22:23], v[40:41], v[22:23] op_sel_hi:[0,1]
	v_pk_mul_f32 v[38:39], v[40:41], v[38:39] op_sel_hi:[0,1]
	v_pk_mul_f32 v[34:35], v[40:41], v[34:35] op_sel_hi:[0,1]
	v_pk_mul_f32 v[16:17], v[46:47], v[16:17]
	v_pk_mul_f32 v[36:37], v[48:49], v[36:37]
	v_pk_mul_f32 v[28:29], v[42:43], v[60:61]
	v_pk_mul_f32 v[22:23], v[22:23], v[62:63]
	v_pk_mul_f32 v[24:25], v[38:39], v[56:57]
	v_pk_mul_f32 v[26:27], v[34:35], v[58:59]
	v_pk_mul_f32 v[16:17], v[16:17], v[28:29]
	v_pk_mul_f32 v[20:21], v[20:21], v[22:23]
	v_pk_mul_f32 v[18:19], v[18:19], v[24:25]
	v_pk_mul_f32 v[22:23], v[36:37], v[26:27]
	v_cvt_pk_bf16_f32 v16, v16, v17
	v_cvt_pk_bf16_f32 v17, v20, v21
	v_cvt_pk_bf16_f32 v18, v18, v19
	v_cvt_pk_bf16_f32 v19, v22, v23
	global_store_dwordx4 v[32:33], v[16:19], off
	s_waitcnt vmcnt(1)
	s_cbranch_scc0 .LBB0_645
